# cross-attention online softmax: 16 score*scale multiplies -> 8 v_pk_mul_f32 and 16 (score*scale - max) fmas -> 8 v_pk_fma_f32 (on top of the packed chunk-attention softmax)
# baseline (speedup 1.0000x reference)
; #define MFMA(a, b, c) __builtin_amdgcn_mfma_f32_32x32x16_bf16((a), (b), (c), 0, 0, 0)
; DI f32x16 zero16() { f32x16 z; for (int i = 0; i < 16; ++i) z[i] = 0.f; return z; }
; DI void phase_xattn(const Params& p, char* lds) {
;     ...
;       f32x16 S = zero16();
; #pragma unroll
;       for (int kk = 0; kk < 16; ++kk) S = MFMA(ldfrag(kl + kk * 16), Qf[kk], S);
;       float mx = -INFINITY;
; #pragma unroll
;       for (int r = 0; r < 16; ++r) { S[r] *= 0.09016844005556021f; mx = fmaxf(mx, S[r]); }
;       mx = fmaxf(mx, __shfl_xor(mx, 32));
;       const float mnew = fmaxf(mrun, mx), alpha = __builtin_amdgcn_exp2f(mrun - mnew);
;       mrun = mnew;
;       float ps = 0.f;
; #pragma unroll
;       for (int r = 0; r < 16; ++r) { const float e = __builtin_amdgcn_exp2f(S[r] - mnew); S[r] = e; ps += e; }
;       lrun = lrun * alpha + ps;
.LBB0_905:
	s_and_b32 s17, s16, 1
	s_mul_i32 s6, s17, 0x4200
	v_add_u32_e32 v187, s6, v182
	ds_read_b128 v[64:67], v187
	ds_read_b128 v[188:191], v187 offset:32
	s_mul_i32 s6, s17, 0x2800
	v_add_u32_e32 v200, s6, v183
	s_and_b32 s6, s16, 7
	s_waitcnt vmcnt(15) lgkmcnt(1)
	v_mfma_f32_32x32x16_bf16 v[64:79], v[64:67], v[92:95], 0
	s_cmp_lg_u32 s6, 7
	s_waitcnt vmcnt(14) lgkmcnt(0)
	v_mfma_f32_32x32x16_bf16 v[64:79], v[188:191], v[96:99], v[64:79]
	ds_read_b128 v[188:191], v187 offset:64
	ds_read_b128 v[192:195], v187 offset:96
	s_waitcnt vmcnt(13) lgkmcnt(1)
	v_mfma_f32_32x32x16_bf16 v[64:79], v[188:191], v[100:103], v[64:79]
	s_waitcnt vmcnt(12) lgkmcnt(0)
	v_mfma_f32_32x32x16_bf16 v[64:79], v[192:195], v[104:107], v[64:79]
	ds_read_b128 v[188:191], v187 offset:128
	ds_read_b128 v[192:195], v187 offset:160
	s_waitcnt vmcnt(11) lgkmcnt(1)
	v_mfma_f32_32x32x16_bf16 v[64:79], v[188:191], v[108:111], v[64:79]
	s_waitcnt vmcnt(10) lgkmcnt(0)
	v_mfma_f32_32x32x16_bf16 v[64:79], v[192:195], v[112:115], v[64:79]
	ds_read_b128 v[188:191], v187 offset:192
	ds_read_b128 v[192:195], v187 offset:224
	s_waitcnt vmcnt(9) lgkmcnt(1)
	v_mfma_f32_32x32x16_bf16 v[64:79], v[188:191], v[116:119], v[64:79]
	s_waitcnt vmcnt(8) lgkmcnt(0)
	v_mfma_f32_32x32x16_bf16 v[64:79], v[192:195], v[120:123], v[64:79]
	ds_read_b128 v[188:191], v187 offset:256
	ds_read_b128 v[192:195], v187 offset:288
	s_waitcnt vmcnt(7) lgkmcnt(1)
	v_mfma_f32_32x32x16_bf16 v[64:79], v[188:191], v[124:127], v[64:79]
	s_waitcnt vmcnt(6) lgkmcnt(0)
	v_mfma_f32_32x32x16_bf16 v[64:79], v[192:195], v[128:131], v[64:79]
	ds_read_b128 v[188:191], v187 offset:320
	ds_read_b128 v[192:195], v187 offset:352
	s_waitcnt vmcnt(5) lgkmcnt(1)
	v_mfma_f32_32x32x16_bf16 v[64:79], v[188:191], v[132:135], v[64:79]
	s_waitcnt vmcnt(4) lgkmcnt(0)
	v_mfma_f32_32x32x16_bf16 v[64:79], v[192:195], v[136:139], v[64:79]
	ds_read_b128 v[188:191], v187 offset:384
	ds_read_b128 v[192:195], v187 offset:416
	s_waitcnt vmcnt(3) lgkmcnt(1)
	v_mfma_f32_32x32x16_bf16 v[64:79], v[188:191], v[140:143], v[64:79]
	s_waitcnt vmcnt(2) lgkmcnt(0)
	v_mfma_f32_32x32x16_bf16 v[64:79], v[192:195], v[144:147], v[64:79]
	ds_read_b128 v[188:191], v187 offset:448
	ds_read_b128 v[192:195], v187 offset:480
	s_waitcnt vmcnt(1) lgkmcnt(1)
	v_mfma_f32_32x32x16_bf16 v[64:79], v[188:191], v[148:151], v[64:79]
	ds_read_b128 v[188:191], v200 offset:33792
	ds_read_b128 v[196:199], v200 offset:33824
	s_waitcnt vmcnt(0) lgkmcnt(2)
	v_mfma_f32_32x32x16_bf16 v[64:79], v[192:195], v[152:155], v[64:79]
	s_nop 11
	s_mov_b32 s98, 0x3db8aa3b
	v_pk_mul_f32 v[228:229], v[64:65], s[98:99] op_sel_hi:[1,0]
	v_pk_mul_f32 v[230:231], v[66:67], s[98:99] op_sel_hi:[1,0]
	v_pk_mul_f32 v[232:233], v[68:69], s[98:99] op_sel_hi:[1,0]
	v_pk_mul_f32 v[234:235], v[70:71], s[98:99] op_sel_hi:[1,0]
	v_pk_mul_f32 v[236:237], v[72:73], s[98:99] op_sel_hi:[1,0]
	v_pk_mul_f32 v[238:239], v[74:75], s[98:99] op_sel_hi:[1,0]
	v_pk_mul_f32 v[240:241], v[76:77], s[98:99] op_sel_hi:[1,0]
	v_pk_mul_f32 v[242:243], v[78:79], s[98:99] op_sel_hi:[1,0]
	v_max3_f32 v187, v228, s12, v229
	v_max3_f32 v187, v187, v230, v231
	v_max3_f32 v187, v187, v232, v233
	v_max3_f32 v187, v187, v234, v235
	v_max3_f32 v187, v187, v236, v237
	v_max3_f32 v187, v187, v238, v239
	v_max3_f32 v187, v187, v240, v241
	v_max3_f32 v187, v187, v242, v243
	ds_bpermute_b32 v201, v184, v187
	ds_read_b128 v[192:195], v200 offset:36352
	ds_read_b128 v[204:207], v200 offset:36384
	ds_read_b128 v[208:211], v200 offset:38912
	ds_read_b128 v[212:215], v200 offset:38944
	s_waitcnt lgkmcnt(4)
	v_max3_f32 v187, v186, v187, v201
	v_pk_fma_f32 v[64:65], v[64:65], s[2:3], v[186:187] op_sel:[0,0,1] op_sel_hi:[1,0,1] neg_lo:[0,0,1] neg_hi:[0,0,1]
	v_exp_f32_e32 v201, v64
	v_pk_fma_f32 v[66:67], v[66:67], s[2:3], v[186:187] op_sel:[0,0,1] op_sel_hi:[1,0,1] neg_lo:[0,0,1] neg_hi:[0,0,1]
	v_exp_f32_e32 v202, v65
	v_exp_f32_e32 v216, v66
	v_pk_fma_f32 v[68:69], v[68:69], s[2:3], v[186:187] op_sel:[0,0,1] op_sel_hi:[1,0,1] neg_lo:[0,0,1] neg_hi:[0,0,1]
	v_pk_fma_f32 v[76:77], v[76:77], s[2:3], v[186:187] op_sel:[0,0,1] op_sel_hi:[1,0,1] neg_lo:[0,0,1] neg_hi:[0,0,1]
	v_exp_f32_e32 v217, v67
	v_exp_f32_e32 v218, v68
	v_exp_f32_e32 v227, v76
	v_add_f32_e32 v76, 0, v201
	v_pk_fma_f32 v[70:71], v[70:71], s[2:3], v[186:187] op_sel:[0,0,1] op_sel_hi:[1,0,1] neg_lo:[0,0,1] neg_hi:[0,0,1]
	v_pk_fma_f32 v[72:73], v[72:73], s[2:3], v[186:187] op_sel:[0,0,1] op_sel_hi:[1,0,1] neg_lo:[0,0,1] neg_hi:[0,0,1]
	v_pk_fma_f32 v[74:75], v[74:75], s[2:3], v[186:187] op_sel:[0,0,1] op_sel_hi:[1,0,1] neg_lo:[0,0,1] neg_hi:[0,0,1]
	v_exp_f32_e32 v219, v69
	v_add_f32_e32 v76, v202, v76
	v_exp_f32_e32 v220, v70
	v_exp_f32_e32 v223, v72
	v_exp_f32_e32 v224, v73
	v_exp_f32_e32 v225, v74
	v_exp_f32_e32 v226, v75
	ds_read_b128 v[72:75], v200 offset:41472
	v_add_f32_e32 v76, v216, v76
	v_exp_f32_e32 v221, v71
	v_add_f32_e32 v76, v217, v76
	v_sub_f32_e32 v186, v186, v187
	v_add_f32_e32 v76, v218, v76
	v_exp_f32_e32 v186, v186
	v_add_f32_e32 v76, v219, v76
	v_add_f32_e32 v76, v220, v76
	v_add_f32_e32 v76, v221, v76
	v_add_f32_e32 v76, v223, v76
	v_pk_fma_f32 v[78:79], v[78:79], s[2:3], v[186:187] op_sel:[0,0,1] op_sel_hi:[1,0,1] neg_lo:[0,0,1] neg_hi:[0,0,1]
	v_cvt_pk_bf16_f32 v64, v201, v202
	v_cvt_pk_bf16_f32 v65, v216, v217
	v_cvt_pk_bf16_f32 v66, v218, v219
	v_cvt_pk_bf16_f32 v67, v220, v221
	v_pk_mul_f32 v[62:63], v[62:63], v[186:187] op_sel_hi:[1,0]
	v_pk_mul_f32 v[60:61], v[60:61], v[186:187] op_sel_hi:[1,0]
	v_pk_mul_f32 v[58:59], v[58:59], v[186:187] op_sel_hi:[1,0]
	v_pk_mul_f32 v[56:57], v[56:57], v[186:187] op_sel_hi:[1,0]
	v_pk_mul_f32 v[54:55], v[54:55], v[186:187] op_sel_hi:[1,0]
; #define MFMA(a, b, c) __builtin_amdgcn_mfma_f32_32x32x16_bf16((a), (b), (c), 0, 0, 0)
; DI unsigned pack2(float a, float b) { const f32x2 v = {a, b}; return __builtin_bit_cast(unsigned, __builtin_convertvector(v, bf16v2)); }
; DI void phase_xattn(const Params& p, char* lds) {
;     ...
;       float ps = 0.f;
; #pragma unroll
;       for (int r = 0; r < 16; ++r) { const float e = __builtin_amdgcn_exp2f(S[r] - mnew); S[r] = e; ps += e; }
;       lrun = lrun * alpha + ps;
;       bf16x8 Pf[2];
; #pragma unroll
;       for (int ks = 0; ks < 2; ++ks) {
;         union { bf16x8 v; unsigned u[4]; } cv;
;         for (int j2 = 0; j2 < 4; ++j2) cv.u[j2] = pack2(S[8 * ks + 2 * j2], S[8 * ks + 2 * j2 + 1]);
;         Pf[ks] = cv.v;
;       }
; #pragma unroll
;       for (int dt = 0; dt < 4; ++dt) {
; #pragma unroll
;         for (int r = 0; r < 16; ++r) O[dt][r] *= alpha;
; #pragma unroll
;         for (int ks = 0; ks < 2; ++ks) O[dt] = MFMA(ldfrag(vl + dt * 32 * 40 + 16 * ks), Pf[ks], O[dt]);
;       }
	v_pk_mul_f32 v[52:53], v[52:53], v[186:187] op_sel_hi:[1,0]
	v_pk_mul_f32 v[50:51], v[50:51], v[186:187] op_sel_hi:[1,0]
	v_pk_mul_f32 v[48:49], v[48:49], v[186:187] op_sel_hi:[1,0]
	v_add_f32_e32 v76, v224, v76
	v_pk_mul_f32 v[14:15], v[14:15], v[186:187] op_sel_hi:[1,0]
	v_pk_mul_f32 v[12:13], v[12:13], v[186:187] op_sel_hi:[1,0]
	v_mfma_f32_32x32x16_bf16 v[48:63], v[188:191], v[64:67], v[48:63]
	v_mul_f32_e64 v10, v10, v186
	v_mul_f32_e64 v11, v11, v186
	v_mul_f32_e64 v8, v8, v186
	v_mul_f32_e64 v9, v9, v186
	v_mul_f32_e64 v6, v6, v186
	v_mul_f32_e64 v7, v7, v186
	v_pk_mul_f32 v[4:5], v[4:5], v[186:187] op_sel_hi:[1,0]
	v_pk_mul_f32 v[2:3], v[2:3], v[186:187] op_sel_hi:[1,0]
	v_pk_mul_f32 v[0:1], v[0:1], v[186:187] op_sel_hi:[1,0]
	v_pk_mul_f32 v[46:47], v[46:47], v[186:187] op_sel_hi:[1,0]
	v_pk_mul_f32 v[44:45], v[44:45], v[186:187] op_sel_hi:[1,0]
	v_pk_mul_f32 v[42:43], v[42:43], v[186:187] op_sel_hi:[1,0]
	v_pk_mul_f32 v[40:41], v[40:41], v[186:187] op_sel_hi:[1,0]
	v_pk_mul_f32 v[38:39], v[38:39], v[186:187] op_sel_hi:[1,0]
	v_pk_mul_f32 v[36:37], v[36:37], v[186:187] op_sel_hi:[1,0]
	v_pk_mul_f32 v[34:35], v[34:35], v[186:187] op_sel_hi:[1,0]
	v_pk_mul_f32 v[32:33], v[32:33], v[186:187] op_sel_hi:[1,0]
	v_exp_f32_e32 v188, v77
	v_exp_f32_e32 v189, v78
	v_exp_f32_e32 v190, v79
	v_pk_mul_f32 v[30:31], v[30:31], v[186:187] op_sel_hi:[1,0]
	v_add_f32_e32 v191, v225, v76
	v_pk_mul_f32 v[28:29], v[28:29], v[186:187] op_sel_hi:[1,0]
	v_pk_mul_f32 v[26:27], v[26:27], v[186:187] op_sel_hi:[1,0]
	v_pk_mul_f32 v[24:25], v[24:25], v[186:187] op_sel_hi:[1,0]
	v_pk_mul_f32 v[22:23], v[22:23], v[186:187] op_sel_hi:[1,0]
	v_pk_mul_f32 v[20:21], v[20:21], v[186:187] op_sel_hi:[1,0]
	v_pk_mul_f32 v[18:19], v[18:19], v[186:187] op_sel_hi:[1,0]
	v_pk_mul_f32 v[16:17], v[16:17], v[186:187] op_sel_hi:[1,0]
	ds_read_b128 v[76:79], v200 offset:41504
	s_waitcnt lgkmcnt(5)
	v_mfma_f32_32x32x16_bf16 v[0:15], v[192:195], v[64:67], v[0:15]
	v_cvt_pk_bf16_f32 v68, v223, v224
	v_cvt_pk_bf16_f32 v69, v225, v226
	v_cvt_pk_bf16_f32 v70, v227, v188
	v_cvt_pk_bf16_f32 v71, v189, v190
	s_waitcnt lgkmcnt(3)
	v_mfma_f32_32x32x16_bf16 v[32:47], v[208:211], v[64:67], v[32:47]
	s_waitcnt lgkmcnt(1)
	v_mfma_f32_32x32x16_bf16 v[16:31], v[72:75], v[64:67], v[16:31]
	v_add_f32_e32 v64, v226, v191
	v_add_f32_e32 v64, v227, v64
	v_add_f32_e32 v64, v188, v64
	v_add_f32_e32 v64, v189, v64
	v_add_f32_e32 v64, v190, v64
	v_fmac_f32_e32 v64, v185, v186
	v_mfma_f32_32x32x16_bf16 v[48:63], v[196:199], v[68:71], v[48:63]
	v_mfma_f32_32x32x16_bf16 v[0:15], v[204:207], v[68:71], v[0:15]
	v_mfma_f32_32x32x16_bf16 v[32:47], v[212:215], v[68:71], v[32:47]
	s_waitcnt lgkmcnt(0)
	v_mfma_f32_32x32x16_bf16 v[16:31], v[76:79], v[68:71], v[16:31]
	s_cbranch_scc1 .LBB0_907
; DI unsigned pack2(float a, float b) { const f32x2 v = {a, b}; return __builtin_bit_cast(unsigned, __builtin_convertvector(v, bf16v2)); }
; DI f32x16 zero16() { f32x16 z; for (int i = 0; i < 16; ++i) z[i] = 0.f; return z; }
; DI void phase_xattn(const Params& p, char* lds) {
;     ...
;       if (kt == 7) {
;         const float inv = __builtin_amdgcn_rcpf(lrun + __shfl_xor(lrun, 32));
; #pragma unroll
;         for (int dt = 0; dt < 4; ++dt) {
; #pragma unroll
;           for (int g = 0; g < 4; ++g) {
;             uint2 o; o.x = pack2(O[dt][4 * g] * inv, O[dt][4 * g + 1] * inv); o.y = pack2(O[dt][4 * g + 2] * inv, O[dt][4 * g + 3] * inv);
;             *(uint2*)(XO + (q0 + l31) * 1024 + h * 256 + dh * 128 + dt * 32 + 8 * g + 4 * hh) = o;
;           }
;           O[dt] = zero16();
;         }
;         mrun = -INFINITY; lrun = 0.f;
;       }
	ds_bpermute_b32 v65, v184, v64
	s_and_b32 s6, s15, 0x80
	s_lshl_b32 s6, s6, 1
	v_lshl_add_u64 v[66:67], v[180:181], 0, s[6:7]
	v_mov_b32_e32 v187, 0xff800000
	s_waitcnt lgkmcnt(0)
	v_add_f32_e32 v64, v64, v65
	v_rcp_f32_e32 v64, v64
	s_nop 0
	v_pk_mul_f32 v[0:1], v[0:1], v[64:65] op_sel_hi:[1,0]
	v_pk_mul_f32 v[2:3], v[2:3], v[64:65] op_sel_hi:[1,0]
	v_cvt_pk_bf16_f32 v0, v0, v1
	v_cvt_pk_bf16_f32 v1, v2, v3
	global_store_dwordx2 v[66:67], v[0:1], off offset:64
	v_pk_mul_f32 v[0:1], v[4:5], v[64:65] op_sel_hi:[1,0]
	v_pk_mul_f32 v[2:3], v[6:7], v[64:65] op_sel_hi:[1,0]
	v_cvt_pk_bf16_f32 v0, v0, v1
	v_cvt_pk_bf16_f32 v1, v2, v3
	global_store_dwordx2 v[66:67], v[0:1], off offset:80
	v_pk_mul_f32 v[0:1], v[8:9], v[64:65] op_sel_hi:[1,0]
	v_pk_mul_f32 v[2:3], v[10:11], v[64:65] op_sel_hi:[1,0]
	v_cvt_pk_bf16_f32 v0, v0, v1
	v_cvt_pk_bf16_f32 v1, v2, v3
	global_store_dwordx2 v[66:67], v[0:1], off offset:96
	v_pk_mul_f32 v[0:1], v[12:13], v[64:65] op_sel_hi:[1,0]
	v_pk_mul_f32 v[2:3], v[14:15], v[64:65] op_sel_hi:[1,0]
	v_cvt_pk_bf16_f32 v0, v0, v1
	v_cvt_pk_bf16_f32 v1, v2, v3
	global_store_dwordx2 v[66:67], v[0:1], off offset:112
	v_pk_mul_f32 v[0:1], v[32:33], v[64:65] op_sel_hi:[1,0]
	v_pk_mul_f32 v[2:3], v[34:35], v[64:65] op_sel_hi:[1,0]
	v_cvt_pk_bf16_f32 v0, v0, v1
	v_cvt_pk_bf16_f32 v1, v2, v3
	global_store_dwordx2 v[66:67], v[0:1], off offset:128
	v_pk_mul_f32 v[0:1], v[36:37], v[64:65] op_sel_hi:[1,0]
	v_pk_mul_f32 v[2:3], v[38:39], v[64:65] op_sel_hi:[1,0]
	v_cvt_pk_bf16_f32 v0, v0, v1
	v_cvt_pk_bf16_f32 v1, v2, v3
	global_store_dwordx2 v[66:67], v[0:1], off offset:144
	v_pk_mul_f32 v[0:1], v[40:41], v[64:65] op_sel_hi:[1,0]
	v_pk_mul_f32 v[2:3], v[42:43], v[64:65] op_sel_hi:[1,0]
	v_cvt_pk_bf16_f32 v0, v0, v1
	v_cvt_pk_bf16_f32 v1, v2, v3
	global_store_dwordx2 v[66:67], v[0:1], off offset:160
	v_pk_mul_f32 v[0:1], v[44:45], v[64:65] op_sel_hi:[1,0]
	v_pk_mul_f32 v[2:3], v[46:47], v[64:65] op_sel_hi:[1,0]
	v_cvt_pk_bf16_f32 v0, v0, v1
	v_cvt_pk_bf16_f32 v1, v2, v3
	v_pk_mul_f32 v[48:49], v[48:49], v[64:65] op_sel_hi:[1,0]
	v_pk_mul_f32 v[50:51], v[50:51], v[64:65] op_sel_hi:[1,0]
	global_store_dwordx2 v[66:67], v[0:1], off offset:176
	v_pk_mul_f32 v[0:1], v[16:17], v[64:65] op_sel_hi:[1,0]
	v_pk_mul_f32 v[2:3], v[18:19], v[64:65] op_sel_hi:[1,0]
	v_cvt_pk_bf16_f32 v48, v48, v49
	v_cvt_pk_bf16_f32 v49, v50, v51
	v_cvt_pk_bf16_f32 v0, v0, v1
	v_cvt_pk_bf16_f32 v1, v2, v3
	v_pk_mul_f32 v[52:53], v[52:53], v[64:65] op_sel_hi:[1,0]
	global_store_dwordx2 v[66:67], v[48:49], off
	v_pk_mul_f32 v[48:49], v[54:55], v[64:65] op_sel_hi:[1,0]
	global_store_dwordx2 v[66:67], v[0:1], off offset:192
	v_pk_mul_f32 v[0:1], v[20:21], v[64:65] op_sel_hi:[1,0]
	v_pk_mul_f32 v[2:3], v[22:23], v[64:65] op_sel_hi:[1,0]
	v_cvt_pk_bf16_f32 v50, v52, v53
	v_cvt_pk_bf16_f32 v51, v48, v49
	v_cvt_pk_bf16_f32 v0, v0, v1
	v_cvt_pk_bf16_f32 v1, v2, v3
	global_store_dwordx2 v[66:67], v[50:51], off offset:16
	v_pk_mul_f32 v[48:49], v[56:57], v[64:65] op_sel_hi:[1,0]
	v_pk_mul_f32 v[50:51], v[58:59], v[64:65] op_sel_hi:[1,0]
	global_store_dwordx2 v[66:67], v[0:1], off offset:208
	v_pk_mul_f32 v[0:1], v[24:25], v[64:65] op_sel_hi:[1,0]
	v_pk_mul_f32 v[2:3], v[26:27], v[64:65] op_sel_hi:[1,0]
	v_cvt_pk_bf16_f32 v48, v48, v49
	v_cvt_pk_bf16_f32 v49, v50, v51
	v_cvt_pk_bf16_f32 v0, v0, v1
	v_cvt_pk_bf16_f32 v1, v2, v3
	global_store_dwordx2 v[66:67], v[48:49], off offset:32
	v_pk_mul_f32 v[48:49], v[60:61], v[64:65] op_sel_hi:[1,0]
	v_pk_mul_f32 v[50:51], v[62:63], v[64:65] op_sel_hi:[1,0]
	global_store_dwordx2 v[66:67], v[0:1], off offset:224
	v_pk_mul_f32 v[0:1], v[28:29], v[64:65] op_sel_hi:[1,0]
	v_pk_mul_f32 v[2:3], v[30:31], v[64:65] op_sel_hi:[1,0]
	v_cvt_pk_bf16_f32 v48, v48, v49
	v_cvt_pk_bf16_f32 v49, v50, v51
	v_cvt_pk_bf16_f32 v0, v0, v1
	v_cvt_pk_bf16_f32 v1, v2, v3
	v_mov_b32_e32 v64, 0
	global_store_dwordx2 v[66:67], v[48:49], off offset:48
	global_store_dwordx2 v[66:67], v[0:1], off offset:240
	v_mov_b32_e32 v0, 0
	v_mov_b32_e32 v1, v64
	v_mov_b32_e32 v2, v64
	v_mov_b32_e32 v3, v64
	v_mov_b32_e32 v4, v64
	v_mov_b32_e32 v5, v64
	v_mov_b32_e32 v6, v64
	v_mov_b32_e32 v7, v64
	v_mov_b32_e32 v8, v64
	v_mov_b32_e32 v9, v64
	v_mov_b32_e32 v10, v64
	v_mov_b32_e32 v11, v64
	v_mov_b32_e32 v12, v64
	v_mov_b32_e32 v13, v64
	v_mov_b32_e32 v14, v64
	v_mov_b32_e32 v15, v64
	v_mov_b32_e32 v48, 0
	v_mov_b32_e32 v49, v64
	v_mov_b32_e32 v50, v64
	v_mov_b32_e32 v51, v64
	v_mov_b32_e32 v52, v64
	v_mov_b32_e32 v53, v64
	v_mov_b32_e32 v54, v64
	v_mov_b32_e32 v55, v64
	v_mov_b32_e32 v56, v64
	v_mov_b32_e32 v57, v64
	v_mov_b32_e32 v58, v64
	v_mov_b32_e32 v59, v64
	v_mov_b32_e32 v60, v64
	v_mov_b32_e32 v61, v64
	v_mov_b32_e32 v62, v64
	v_mov_b32_e32 v63, v64
	v_mov_b32_e32 v32, 0
	v_mov_b32_e32 v33, v64
	v_mov_b32_e32 v34, v64
	v_mov_b32_e32 v35, v64
	v_mov_b32_e32 v36, v64
	v_mov_b32_e32 v37, v64
	v_mov_b32_e32 v38, v64
	v_mov_b32_e32 v39, v64
	v_mov_b32_e32 v40, v64
	v_mov_b32_e32 v41, v64
	v_mov_b32_e32 v42, v64
	v_mov_b32_e32 v43, v64
	v_mov_b32_e32 v44, v64
	v_mov_b32_e32 v45, v64
	v_mov_b32_e32 v46, v64
	v_mov_b32_e32 v47, v64
	v_mov_b32_e32 v16, 0
	v_mov_b32_e32 v17, v64
	v_mov_b32_e32 v18, v64
	v_mov_b32_e32 v19, v64
	v_mov_b32_e32 v20, v64
	v_mov_b32_e32 v21, v64
	v_mov_b32_e32 v22, v64
	v_mov_b32_e32 v23, v64
	v_mov_b32_e32 v24, v64
	v_mov_b32_e32 v25, v64
	v_mov_b32_e32 v26, v64
	v_mov_b32_e32 v27, v64
	v_mov_b32_e32 v28, v64
	v_mov_b32_e32 v29, v64
	v_mov_b32_e32 v30, v64
	v_mov_b32_e32 v31, v64
